# attention Q-fragment loads streamed (nt): read-once data no longer displaces the K/V tiles other units re-read from L2
# baseline (speedup 1.0000x reference)
; #define LAS __attribute__((address_space(3)))
; #define LOAD_QF(qw_) do { const bf16_t* qp = QI + ((size_t)(bh * 64 + ((qw_) >> 5))) * 6144 + lane * 8; \
;         _Pragma("unroll") for (int ks = 0; ks < 12; ++ks) qf[ks] = *(const bf16x8*)(qp + ks * 512); } while (0)
; __device__ __forceinline__ void attn_phase(const Ptrs& P, LAS unsigned char* lds, int vcu) {
;     const int tid = threadIdx.x, lane = tid & 63, wid = __builtin_amdgcn_readfirstlane(tid >> 6), r32 = lane & 31, hi = lane >> 5;
;     const bf16_t* QI = (const bf16_t*)(P.ws + WS_QIMG); const bf16_t* KN = (const bf16_t*)(P.ws + WS_RA); const bf16_t* KPE = (const bf16_t*)(P.ws + WS_KPE); const bf16_t* VI = (const bf16_t*)(P.ws + WS_VIMG);
;     bf16_t* A2 = (bf16_t*)(P.ws + WS_A2);
;     const int bh = vcu >> 1, b = bh >> 3, head = bh & 7;
;     const bf16_t* kn_b = KN + (size_t)bh * 64 * 4096 + lane * 8; const bf16_t* kpe_b = KPE + (size_t)b * 64 * 2048 + lane * 8; const bf16_t* v_b = VI + (size_t)bh * 256 * 1024 + lane * 8;
;     LAS unsigned char* const wz = lds + 2 * ATT_STAGE + wid * 8192;
;     const int vb = 24576 + (4 * hi + ((lane & 15) >> 2)) * 64 + ((lane >> 4) & 1) * 32 + (lane & 3) * 8;
;     ...
;     bf16x8 qf[12];
;     ISSUE_TILE(0, 0);
;     LOAD_QF(QB_OF(0) * 256 + 32 * wid);
.LBB0_1155:
	s_lshl_b32 s14, s17, 13
	s_lshl_b32 s75, s19, 10
	s_add_i32 s14, s14, 0
	s_add_i32 s84, s75, 0
	s_add_i32 s23, s14, 0x14000
	s_lshl_b32 s19, s10, 6
	s_and_b32 s14, s87, 1
	s_bitcmp1_b32 s87, 0
	v_writelane_b32 v254, s87, 54
	s_cselect_b64 s[4:5], -1, 0
	v_writelane_b32 v254, s4, 55
	s_cmp_eq_u32 s14, 0
	s_mov_b32 m0, s84
	v_writelane_b32 v254, s5, 56
	s_cselect_b64 s[4:5], -1, 0
	v_writelane_b32 v254, s4, 57
	s_and_b64 s[14:15], s[4:5], exec
	s_cselect_b32 s14, 56, 40
	s_or_b32 s14, s14, s19
	s_add_i32 s14, s14, s17
	global_load_lds_dwordx4 v[4:5], off
	v_mad_i64_i32 v[4:5], s[14:15], s14, v219, v[184:185]
	s_movk_i32 s14, 0x1000
	s_nop 0
	v_add_co_u32_e32 v6, vcc, s14, v4
	s_movk_i32 s14, 0x2000
	s_nop 0
	v_addc_co_u32_e32 v7, vcc, 0, v5, vcc
	global_load_dwordx4 v[128:131], v[4:5], off nt
	global_load_dwordx4 v[132:135], v[4:5], off offset:1024 nt
	global_load_dwordx4 v[136:139], v[4:5], off offset:2048 nt
	global_load_dwordx4 v[140:143], v[4:5], off offset:3072 nt
	v_add_co_u32_e32 v4, vcc, s14, v4
	v_writelane_b32 v254, s5, 58
	s_nop 0
	v_addc_co_u32_e32 v5, vcc, 0, v5, vcc
	global_load_dwordx4 v[144:147], v[6:7], off offset:1024 nt
	global_load_dwordx4 v[152:155], v[6:7], off offset:2048 nt
	global_load_dwordx4 v[148:151], v[4:5], off offset:-4096 nt
	global_load_dwordx4 v[156:159], v[6:7], off offset:3072 nt
	global_load_dwordx4 v[160:163], v[4:5], off nt
	global_load_dwordx4 v[164:167], v[4:5], off offset:1024 nt
	global_load_dwordx4 v[168:171], v[4:5], off offset:2048 nt
	global_load_dwordx4 v[172:175], v[4:5], off offset:3072 nt
	s_lshl_b32 s4, s12, 11
	s_lshl_b32 s10, s10, 7
	s_lshl_b32 s28, s17, 5
	v_writelane_b32 v254, s4, 59
	s_and_b32 s22, s10, 0x380
	s_add_i32 s4, s17, s19
	s_cmpk_gt_u32 s16, 0x13f
	s_cselect_b64 s[96:97], -1, 0
	s_cmpk_lt_u32 s16, 0x140
	v_writelane_b32 v254, s4, 60
	s_cselect_b64 vcc, -1, 0
	s_add_i32 s4, s20, 0xffffd000
	s_mov_b32 s5, s73
	v_writelane_b32 v254, s4, 61
	s_lshl_b32 s10, s11, 9
	s_add_i32 s16, s10, 0xffffd000
	v_writelane_b32 v254, s5, 62
	s_mov_b32 s17, s73
	s_lshl_b32 s88, s13, 9
	v_writelane_b32 v254, s16, 63
	s_add_i32 s12, s88, 0xffffd000
	s_mov_b32 s13, s73
	v_writelane_b32 v255, s17, 0
	v_writelane_b32 v255, s12, 1
	s_lshl_b32 s68, s18, 9
	s_add_i32 s18, s68, 0xffffd000
	v_writelane_b32 v255, s13, 2
	s_mov_b32 s19, s73
	s_mov_b32 s14, s20
	s_mov_b32 s15, s73
	v_writelane_b32 v255, s18, 3
	v_lshl_add_u64 v[4:5], s[4:5], 1, v[188:189]
	s_mov_b64 s[4:5], s[14:15]
	s_lshl_b64 s[14:15], s[14:15], 1
	s_movk_i32 s24, 0xc000
	s_mov_b32 s11, s73
	v_writelane_b32 v255, s19, 4
	s_add_i32 s20, s72, 0xffffd000
	s_mov_b32 s21, s73
	v_lshl_add_u64 v[6:7], v[2:3], 0, s[14:15]
	s_mov_b32 s25, -1
	v_lshl_add_u64 v[10:11], s[16:17], 1, v[188:189]
	s_lshl_b64 s[16:17], s[10:11], 1
	s_mov_b32 s89, s73
	v_writelane_b32 v255, s20, 5
	v_lshl_add_u64 v[6:7], v[6:7], 0, s[24:25]
	v_lshl_add_u64 v[12:13], v[2:3], 0, s[16:17]
	v_lshl_add_u64 v[16:17], s[12:13], 1, v[188:189]
	s_lshl_b64 s[12:13], s[88:89], 1
	s_mov_b32 s69, s73
	v_writelane_b32 v255, s21, 6
	v_lshl_add_u64 v[28:29], s[20:21], 1, v[188:189]
	v_readlane_b32 s20, v254, 52
	v_lshl_add_u64 v[8:9], v[190:191], 0, s[14:15]
	v_lshl_add_u64 v[12:13], v[12:13], 0, s[24:25]
	v_lshl_add_u64 v[18:19], v[2:3], 0, s[12:13]
	v_lshl_add_u64 v[22:23], s[18:19], 1, v[188:189]
	s_lshl_b64 s[18:19], s[68:69], 1
	v_readlane_b32 s21, v254, 53
	v_cndmask_b32_e32 v0, v4, v6, vcc
	v_lshl_add_u64 v[14:15], v[190:191], 0, s[16:17]
	v_lshl_add_u64 v[18:19], v[18:19], 0, s[24:25]
	v_lshl_add_u64 v[24:25], v[2:3], 0, s[18:19]
	s_lshl_b64 s[20:21], s[20:21], 1
	v_cndmask_b32_e64 v192, v0, v8, s[6:7]
	v_cndmask_b32_e32 v0, v10, v12, vcc
	v_lshl_add_u64 v[20:21], v[190:191], 0, s[12:13]
	v_lshl_add_u64 v[24:25], v[24:25], 0, s[24:25]
	v_lshl_add_u64 v[2:3], v[2:3], 0, s[20:21]
	v_cndmask_b32_e64 v194, v0, v14, s[8:9]
	v_cndmask_b32_e32 v0, v16, v18, vcc
	v_lshl_add_u64 v[26:27], v[190:191], 0, s[18:19]
	v_lshl_add_u64 v[2:3], v[2:3], 0, s[24:25]
	v_cndmask_b32_e32 v4, v5, v7, vcc
	v_cndmask_b32_e64 v196, v0, v20, s[8:9]
	v_cndmask_b32_e32 v0, v22, v24, vcc
	v_cndmask_b32_e64 v193, v4, v9, s[6:7]
	v_cndmask_b32_e64 v198, v0, v26, s[8:9]
	v_cndmask_b32_e64 v0, v28, v2, s[6:7]
	v_cndmask_b32_e64 v2, v29, v3, s[6:7]
	s_add_u32 s6, s0, s14
	s_addc_u32 s7, s1, s15
	v_lshl_add_u64 v[204:205], v[186:187], 0, s[6:7]
	s_add_u32 s6, s0, s16
	s_addc_u32 s7, s1, s17
	v_lshl_add_u64 v[206:207], v[186:187], 0, s[6:7]
	s_add_u32 s6, s0, s12
	s_addc_u32 s7, s1, s13
	v_lshl_add_u64 v[208:209], v[186:187], 0, s[6:7]
	s_add_u32 s6, s0, s18
	s_addc_u32 s7, s1, s19
	s_add_u32 s0, s0, s20
	s_addc_u32 s1, s1, s21
	v_writelane_b32 v255, s28, 7
	v_lshl_add_u64 v[212:213], v[186:187], 0, s[0:1]
	s_lshl_b32 s0, s22, 1
	v_writelane_b32 v255, s0, 8
	s_add_i32 s0, s23, 0x400
	v_writelane_b32 v255, s0, 9
	s_add_i32 s0, s23, 0x800
	v_writelane_b32 v255, s0, 10
	s_add_i32 s0, s23, 0xc00
	v_cndmask_b32_e32 v4, v11, v13, vcc
	v_writelane_b32 v255, s0, 11
	s_add_i32 s0, s23, 0x1800
	v_cndmask_b32_e64 v195, v4, v15, s[8:9]
	v_cndmask_b32_e32 v4, v17, v19, vcc
	v_writelane_b32 v255, s0, 12
	s_add_i32 s0, s23, 0x1c00
	v_lshl_add_u64 v[30:31], v[190:191], 0, s[20:21]
	v_cndmask_b32_e64 v197, v4, v21, s[8:9]
	v_cndmask_b32_e32 v4, v23, v25, vcc
	v_writelane_b32 v255, s0, 13
	s_mov_b32 s85, 0
	v_add_u32_e32 v221, s23, v217
	v_cndmask_b32_e64 v199, v4, v27, s[8:9]
	v_cndmask_b32_e64 v203, v2, v31, s[8:9]
	v_cndmask_b32_e64 v202, v0, v30, s[8:9]
	v_add_u32_e32 v222, s28, v218
	v_lshl_add_u64 v[210:211], v[186:187], 0, s[6:7]
	v_writelane_b32 v255, s23, 14
	s_branch .LBB0_1157

; #define LOAD_QF(qw_) do { const bf16_t* qp = QI + ((size_t)(bh * 64 + ((qw_) >> 5))) * 6144 + lane * 8; \
;         _Pragma("unroll") for (int ks = 0; ks < 12; ++ks) qf[ks] = *(const bf16x8*)(qp + ks * 512); } while (0)
; __device__ __forceinline__ void attn_phase(const Ptrs& P, LAS unsigned char* lds, int vcu) {
;     ...
;         { auto rr = __builtin_amdgcn_permlane32_swap(__float_as_uint(lrun), __float_as_uint(lrun), false, false); lrun = __uint_as_float(rr[0]) + __uint_as_float(rr[1]); }
;         if (ui + 1 < 4) LOAD_QF(QB_OF(ui + 1) * 256 + 32 * wid);
.LBB0_1231:
	v_mov_b32_e32 v0, v10
	s_nop 1
	v_permlane32_swap_b32_e32 v10, v0
	s_add_i32 s0, s85, 1
	s_and_b64 vcc, exec, s[94:95]
	s_cbranch_vccz .LBB0_1156
	s_cmp_eq_u32 s0, 2
	s_cselect_b32 s1, 32, 24
	s_cselect_b32 s6, 48, 8
	s_cmp_eq_u32 s85, 0
	s_cselect_b32 s8, 0, s6
	v_readlane_b32 s6, v254, 57
	v_readlane_b32 s7, v254, 58
	s_cselect_b32 s1, 16, s1
	s_and_b64 s[6:7], s[6:7], exec
	s_cselect_b32 s1, s8, s1
	v_readlane_b32 s6, v254, 60
	s_add_i32 s1, s6, s1
	v_mad_i64_i32 v[2:3], s[6:7], s1, v219, v[184:185]
	v_add_co_u32_e32 v4, vcc, 0x1000, v2
	global_load_dwordx4 v[128:131], v[2:3], off nt
	global_load_dwordx4 v[132:135], v[2:3], off offset:1024 nt
	global_load_dwordx4 v[136:139], v[2:3], off offset:2048 nt
	global_load_dwordx4 v[140:143], v[2:3], off offset:3072 nt
	v_addc_co_u32_e32 v5, vcc, 0, v3, vcc
	v_add_co_u32_e32 v2, vcc, 0x2000, v2
	global_load_dwordx4 v[148:151], v[4:5], off nt
	global_load_dwordx4 v[144:147], v[4:5], off offset:1024 nt
	global_load_dwordx4 v[152:155], v[4:5], off offset:2048 nt
	global_load_dwordx4 v[156:159], v[4:5], off offset:3072 nt
	v_addc_co_u32_e32 v3, vcc, 0, v3, vcc
	global_load_dwordx4 v[160:163], v[2:3], off nt
	global_load_dwordx4 v[164:167], v[2:3], off offset:1024 nt
	global_load_dwordx4 v[168:171], v[2:3], off offset:2048 nt
	global_load_dwordx4 v[172:175], v[2:3], off offset:3072 nt
	s_branch .LBB0_1156
